# MLA K/V tile pointers made absolute per unit; loop uses global_load without per-tile 64-bit address adds
# speedup vs baseline: 1.0061x; 1.0003x over previous
; DI float xhalf_sum(float m) { auto rr = __builtin_amdgcn_permlane32_swap(__float_as_uint(m), __float_as_uint(m), false, false); return __uint_as_float(rr[0]) + __uint_as_float(rr[1]); }
; template <int DQK, int DV, bool CAUSAL, int KT, bool PRIO>
; DI void attn_unit(const bf16_t* Qb, int qpitch, const bf16_t* Kb, int kpitch, const bf16_t* Vtb, int vpitch, bf16_t* Ob, int opitch, int q0, int nt, LAS unsigned char* lds, float kbound, const float* qgain, const int* qpos, float qscale) {
;     ...
;     if (PRIO) {
;         float q2 = 0.f;
; #pragma unroll
;         for (int ks = 0; ks < DQK / 16; ++ks)
; #pragma unroll
;             for (int e = 0; e < 8; ++e) { const float v = __uint_as_float(((unsigned)(unsigned short)qf[ks][e]) << 16); q2 += v * v; }
;         q2 = xhalf_sum(q2);
;         nomax = __all(sqrtf(q2) * kbound <= 100.0f) != 0;
.LBB0_1486:
	s_waitcnt vmcnt(0) lgkmcnt(0)
	v_and_b32_e32 v9, 0xffff0000, v116
	v_lshlrev_b32_e32 v8, 16, v116
	v_mul_f32_e32 v11, v9, v9
	v_fmac_f32_e32 v11, v8, v8
	v_lshlrev_b32_e32 v8, 16, v117
	v_fmac_f32_e32 v11, v8, v8
	v_and_b32_e32 v8, 0xffff0000, v117
	v_fmac_f32_e32 v11, v8, v8
	v_lshlrev_b32_e32 v8, 16, v118
	v_fmac_f32_e32 v11, v8, v8
	v_and_b32_e32 v8, 0xffff0000, v118
	v_fmac_f32_e32 v11, v8, v8
	v_lshlrev_b32_e32 v8, 16, v119
	v_fmac_f32_e32 v11, v8, v8
	v_and_b32_e32 v8, 0xffff0000, v119
	v_fmac_f32_e32 v11, v8, v8
	v_lshlrev_b32_e32 v8, 16, v120
	v_fmac_f32_e32 v11, v8, v8
	v_and_b32_e32 v8, 0xffff0000, v120
	v_fmac_f32_e32 v11, v8, v8
	v_lshlrev_b32_e32 v8, 16, v121
	v_fmac_f32_e32 v11, v8, v8
	v_and_b32_e32 v8, 0xffff0000, v121
	v_fmac_f32_e32 v11, v8, v8
	v_lshlrev_b32_e32 v8, 16, v122
	v_fmac_f32_e32 v11, v8, v8
	v_and_b32_e32 v8, 0xffff0000, v122
	v_fmac_f32_e32 v11, v8, v8
	v_lshlrev_b32_e32 v8, 16, v123
	v_fmac_f32_e32 v11, v8, v8
	v_and_b32_e32 v8, 0xffff0000, v123
	v_fmac_f32_e32 v11, v8, v8
	v_lshlrev_b32_e32 v8, 16, v124
	v_fmac_f32_e32 v11, v8, v8
	v_and_b32_e32 v8, 0xffff0000, v124
	v_fmac_f32_e32 v11, v8, v8
	v_lshlrev_b32_e32 v8, 16, v125
	v_fmac_f32_e32 v11, v8, v8
	v_and_b32_e32 v8, 0xffff0000, v125
	v_fmac_f32_e32 v11, v8, v8
	v_lshlrev_b32_e32 v8, 16, v126
	v_fmac_f32_e32 v11, v8, v8
	v_and_b32_e32 v8, 0xffff0000, v126
	v_fmac_f32_e32 v11, v8, v8
	v_lshlrev_b32_e32 v8, 16, v127
	v_fmac_f32_e32 v11, v8, v8
	v_and_b32_e32 v8, 0xffff0000, v127
	v_fmac_f32_e32 v11, v8, v8
	v_lshlrev_b32_e32 v8, 16, v128
	v_fmac_f32_e32 v11, v8, v8
	v_and_b32_e32 v8, 0xffff0000, v128
	v_fmac_f32_e32 v11, v8, v8
	v_lshlrev_b32_e32 v8, 16, v129
	v_fmac_f32_e32 v11, v8, v8
	v_and_b32_e32 v8, 0xffff0000, v129
	v_fmac_f32_e32 v11, v8, v8
	v_lshlrev_b32_e32 v8, 16, v130
	v_fmac_f32_e32 v11, v8, v8
	v_and_b32_e32 v8, 0xffff0000, v130
	v_fmac_f32_e32 v11, v8, v8
	v_lshlrev_b32_e32 v8, 16, v131
	v_fmac_f32_e32 v11, v8, v8
	v_and_b32_e32 v8, 0xffff0000, v131
	v_fmac_f32_e32 v11, v8, v8
	v_lshlrev_b32_e32 v8, 16, v132
	v_fmac_f32_e32 v11, v8, v8
	v_and_b32_e32 v8, 0xffff0000, v132
	v_fmac_f32_e32 v11, v8, v8
	v_lshlrev_b32_e32 v8, 16, v133
	v_fmac_f32_e32 v11, v8, v8
	v_and_b32_e32 v8, 0xffff0000, v133
	v_fmac_f32_e32 v11, v8, v8
	v_lshlrev_b32_e32 v8, 16, v134
	v_fmac_f32_e32 v11, v8, v8
	v_and_b32_e32 v8, 0xffff0000, v134
	v_fmac_f32_e32 v11, v8, v8
	v_lshlrev_b32_e32 v8, 16, v135
	v_fmac_f32_e32 v11, v8, v8
	v_and_b32_e32 v8, 0xffff0000, v135
	v_fmac_f32_e32 v11, v8, v8
	v_lshlrev_b32_e32 v8, 16, v136
	v_fmac_f32_e32 v11, v8, v8
	v_and_b32_e32 v8, 0xffff0000, v136
	v_fmac_f32_e32 v11, v8, v8
	v_and_b32_e32 v9, 0xffff0000, v137
	v_lshlrev_b32_e32 v8, 16, v137
	v_pk_mul_f32 v[8:9], v[8:9], v[8:9]
	s_xor_b64 s[34:35], s[2:3], -1
	v_add_f32_e32 v8, v8, v11
	v_add_f32_e32 v11, v9, v8
	v_and_b32_e32 v9, 0xffff0000, v138
	v_lshlrev_b32_e32 v8, 16, v138
	v_pk_mul_f32 v[8:9], v[8:9], v[8:9]
	v_mad_i64_i32 v[2:3], s[2:3], v149, s88, 0
	v_add_f32_e32 v8, v8, v11
	v_add_f32_e32 v11, v9, v8
	v_and_b32_e32 v9, 0xffff0000, v139
	v_lshlrev_b32_e32 v8, 16, v139
	v_pk_mul_f32 v[8:9], v[8:9], v[8:9]
	v_mad_i64_i32 v[4:5], s[2:3], v151, s88, 0
	v_add_f32_e32 v8, v8, v11
	v_add_f32_e32 v8, v9, v8
	v_mov_b32_e32 v9, v8
	s_nop 1
	v_permlane32_swap_b32_e32 v8, v9
	v_add_f32_e32 v8, v8, v9
	v_mul_f32_e32 v9, 0x4f800000, v8
	v_cmp_gt_f32_e32 vcc, s91, v8
	v_mad_i64_i32 v[6:7], s[2:3], v153, s88, 0
	s_nop 0
	v_cndmask_b32_e32 v8, v8, v9, vcc
	v_sqrt_f32_e32 v9, v8
	s_add_i32 s2, s38, 0x100
	s_lshr_b32 s68, s2, 7
	v_mul_lo_u32 v178, v149, s53
	v_add_u32_e32 v11, -1, v9
	v_fma_f32 v12, -v11, v9, v8
	v_cmp_ge_f32_e64 s[2:3], 0, v12
	v_add_u32_e32 v12, 1, v9
	v_lshlrev_b32_e32 v179, 4, v150
	v_cndmask_b32_e64 v11, v9, v11, s[2:3]
	v_fma_f32 v9, -v12, v9, v8
	v_cmp_lt_f32_e64 s[2:3], 0, v9
; #define LAS __attribute__((address_space(3)))
; template <int DQK, int DV, bool CAUSAL, int KT, bool PRIO>
; DI void attn_unit(const bf16_t* Qb, int qpitch, const bf16_t* Kb, int kpitch, const bf16_t* Vtb, int vpitch, bf16_t* Ob, int opitch, int q0, int nt, LAS unsigned char* lds, float kbound, const float* qgain, const int* qpos, float qscale) {
;     ...
;     auto gload = [&](int kt) {
; #pragma unroll
;         for (int i = 0; i < NKR; ++i) { const int c = tid + i * 512; if (NKC % 512 == 0 || c < NKC) kreg[i] = *(const u32x4*)(Kb + (size_t)(kt * KT + c / KCH) * kpitch + (c % KCH) * 8); }
; #pragma unroll
;         for (int i = 0; i < NVR; ++i) { const int c = tid + i * 512; vreg[i] = *(const u32x4*)(Vtb + (size_t)(c / VCH) * vpitch + kt * KT + (c % VCH) * 8); }
;     };
;     auto lstore = [&](int buf) {
; #pragma unroll
;         for (int i = 0; i < NKR; ++i) { const int c = tid + i * 512; if (NKC % 512 == 0 || c < NKC) *(LAS u32x4*)(lds + buf * KBUF + (c / KCH) * KS + (c % KCH) * 16) = kreg[i]; }
; #pragma unroll
;         for (int i = 0; i < NVR; ++i) { const int c = tid + i * 512; LAS unsigned char* p = lds + VOFF + buf * VBUF + (c / VCH) * VS + (c % VCH) * 16;
;             *(LAS u32x2*)p = (u32x2){vreg[i].x, vreg[i].y}; *(LAS u32x2*)(p + 8) = (u32x2){vreg[i].z, vreg[i].w}; }
;     };
;     ...
;     lstore(0);
;     __syncthreads();
;     const int qabs = q0 + 32 * w + r, qlo = q0 + 32 * w;
;     for (int kt = 0; kt < nt; ++kt) {
;         const int buf = kt & 1;
;         if (kt + 1 < nt) gload(kt + 1);
	v_mul_lo_u32 v181, v151, s53
	v_lshlrev_b32_e32 v182, 4, v152
	v_cndmask_b32_e64 v9, v11, v12, s[2:3]
	v_mul_f32_e32 v11, 0x37800000, v9
	v_cndmask_b32_e32 v9, v9, v11, vcc
	v_cmp_class_f32_e32 vcc, v8, v176
	v_mul_lo_u32 v183, v153, s53
	v_lshlrev_b32_e32 v184, 4, v154
	v_cndmask_b32_e32 v8, v9, v8, vcc
	v_mul_f32_e32 v8, v174, v8
	v_cmp_ge_f32_e32 vcc, s52, v8
	v_add3_u32 v8, 0, v178, v179
	ds_write_b128 v8, v[96:99]
	v_add3_u32 v8, 0, v181, v182
	ds_write_b128 v8, v[100:103]
	v_add3_u32 v8, 0, v183, v184
	v_mul_lo_u32 v185, v68, s56
	ds_write_b128 v8, v[104:107]
	v_add_u32_e32 v8, 0, v185
	v_and_b32_e32 v186, 1, v69
	v_lshlrev_b32_e32 v186, 3, v186
	v_sub_u32_e32 v186, 0, v186
	v_lshl_add_u32 v186, v69, 4, v186
	v_add3_u32 v8, v8, v186, s57
	v_mul_lo_u32 v187, v74, s56
	ds_write2_b64 v8, v[108:109], v[110:111] offset1:2
	v_add_u32_e32 v8, 0, v187
	v_and_b32_e32 v188, 1, v75
	v_lshlrev_b32_e32 v188, 3, v188
	v_sub_u32_e32 v188, 0, v188
	v_lshl_add_u32 v188, v75, 4, v188
	v_and_b32_e32 v10, 31, v155
	v_add3_u32 v8, v8, v188, s57
	s_ashr_i32 s27, s26, 31
	s_and_b32 s69, s39, 0xffffffe0
	ds_write2_b64 v8, v[112:113], v[114:115] offset1:2
	v_mul_u32_u24_e32 v8, 0x110, v10
	s_cmp_lg_u64 vcc, exec
	v_add3_u32 v191, v0, v8, v0
	v_lshl_add_u64 v[8:9], s[22:23], 0, v[70:71]
	s_cselect_b64 s[2:3], -1, 0
	s_add_i32 s69, s69, s38
	v_lshl_add_u64 v[164:165], v[72:73], 1, v[8:9]
	v_lshl_add_u64 v[8:9], s[22:23], 0, v[64:65]
	v_lshl_add_u64 v[6:7], s[24:25], 0, v[6:7]
	v_lshl_add_u64 v[4:5], s[24:25], 0, v[4:5]
	v_lshl_add_u64 v[2:3], s[24:25], 0, v[2:3]
	v_mov_b32_e32 v14, v1
	v_mov_b32_e32 v15, v1
	v_or_b32_e32 v189, s69, v10
	v_mul_u32_u24_e32 v192, 0xd0, v10
	v_lshl_add_u64 v[166:167], v[66:67], 1, v[8:9]
	v_lshl_add_u64 v[168:169], v[62:63], 1, v[6:7]
	v_lshl_add_u64 v[170:171], v[60:61], 1, v[4:5]
	v_lshl_add_u64 v[172:173], v[58:59], 1, v[2:3]
	v_lshl_add_u64 v[164:165], s[4:5], 0, v[164:165]
	v_lshl_add_u64 v[166:167], s[4:5], 0, v[166:167]
	v_lshl_add_u64 v[168:169], s[4:5], 0, v[168:169]
	v_lshl_add_u64 v[170:171], s[4:5], 0, v[170:171]
	v_lshl_add_u64 v[172:173], s[4:5], 0, v[172:173]
	v_mov_b32_e32 v0, v1
	v_mov_b32_e32 v2, v1
	v_mov_b32_e32 v3, v1
	v_mov_b32_e32 v4, v1
	v_mov_b32_e32 v5, v1
	v_mov_b32_e32 v6, v1
	v_mov_b32_e32 v7, v1
	v_mov_b32_e32 v8, v1
	v_mov_b32_e32 v9, v1
	v_mov_b32_e32 v10, v1
	v_mov_b32_e32 v11, v1
	v_mov_b32_e32 v12, v1
	v_mov_b32_e32 v13, v1
	v_mov_b64_e32 v[30:31], v[14:15]
	v_mov_b64_e32 v[46:47], v[14:15]
	v_mov_b64_e32 v[62:63], v[14:15]
	s_mov_b32 s12, 0
	s_or_b32 s70, s69, 31
	v_lshl_add_u32 v190, v148, 4, 0
	v_lshlrev_b32_e32 v180, 2, v148
	s_mov_b64 s[40:41], -1
	v_mov_b32_e32 v193, 0
	s_mov_b32 s71, 63
	v_mov_b64_e32 v[28:29], v[12:13]
	v_mov_b64_e32 v[26:27], v[10:11]
	v_mov_b64_e32 v[24:25], v[8:9]
	v_mov_b64_e32 v[22:23], v[6:7]
	v_mov_b64_e32 v[20:21], v[4:5]
	v_mov_b64_e32 v[18:19], v[2:3]
	v_mov_b64_e32 v[16:17], v[0:1]
	v_mov_b64_e32 v[44:45], v[12:13]
	v_mov_b64_e32 v[42:43], v[10:11]
	v_mov_b64_e32 v[40:41], v[8:9]
	v_mov_b64_e32 v[38:39], v[6:7]
	v_mov_b64_e32 v[36:37], v[4:5]
	v_mov_b64_e32 v[34:35], v[2:3]
	v_mov_b64_e32 v[32:33], v[0:1]
	v_mov_b64_e32 v[60:61], v[12:13]
	v_mov_b64_e32 v[58:59], v[10:11]
	v_mov_b64_e32 v[56:57], v[8:9]
	v_mov_b64_e32 v[54:55], v[6:7]
	v_mov_b64_e32 v[52:53], v[4:5]
	v_mov_b64_e32 v[50:51], v[2:3]
	v_mov_b64_e32 v[48:49], v[0:1]
	v_mov_b32_e32 v0, 0
	s_waitcnt lgkmcnt(0)
	s_barrier
.LBB0_1487:
	s_add_i32 s74, s12, 1
	s_cmp_lt_u32 s74, s68
	s_cselect_b64 s[38:39], -1, 0
	s_cmp_ge_u32 s74, s68
	s_cbranch_scc1 .LBB0_1489
	s_waitcnt vmcnt(0)
	global_load_dwordx4 v[96:99], v[172:173], off
	global_load_dwordx4 v[100:103], v[170:171], off
	global_load_dwordx4 v[104:107], v[168:169], off
	global_load_dwordx4 v[108:111], v[166:167], off
	global_load_dwordx4 v[112:115], v[164:165], off
